# in-proj: per-unit s_waitcnt vmcnt(0) in front of the K loop removed (rope loads are always drained inside the epilogue; it only waited for the epilogue stores)
# baseline (speedup 1.0000x reference)
; #define G8_STAGE(bufoff, gbase, voff) do { const char* _gb = uptr((const char*)(gbase)); _Pragma("unroll") for (int _i = 0; _i < 2; ++_i) \
;         __builtin_amdgcn_global_load_lds((const unsigned*)(_gb + (voff)[_i]), (LAS unsigned*)(lds + (bufoff) + ldsw + _i * 8192), 16, 0, 0); } while (0)
; #define G8_LDA(dst, b, h) do { _Pragma("unroll") for (int m = 0; m < 4; ++m) _Pragma("unroll") for (int k = 0; k < 2; ++k) dst[m][k] = *(const LAS bf16x8*)(lds + G8_SA(b, h) + aoff + m * 2048 + k * 1024); } while (0)
; #define G8_LDB(dst, b, h) do { _Pragma("unroll") for (int n = 0; n < 2; ++n) _Pragma("unroll") for (int k = 0; k < 2; ++k) dst[n][k] = *(const LAS bf16x8*)(lds + G8_SB(b, h) + boff + n * 2048 + k * 1024); } while (0)
; #define G8_MMA(ai, bj, At, Bt_) do { __builtin_amdgcn_s_setprio(1); _Pragma("unroll") for (int m = 0; m < 4; ++m) _Pragma("unroll") for (int n = 0; n < 2; ++n) _Pragma("unroll") for (int k = 0; k < 2; ++k) \
;         acc[ai][bj][m][n] = __builtin_amdgcn_mfma_f32_16x16x32_bf16(Bt_[n][k], At[m][k], acc[ai][bj][m][n], 0, 0, 0); __builtin_amdgcn_s_setprio(0); } while (0)
; #define G8_WAIT_L(n) asm volatile("s_waitcnt lgkmcnt(" #n ")" ::: "memory")
; #define G8_BAR __builtin_amdgcn_s_barrier()
;     ...
;         const bool has_next = next_unit<NKH, ROT>(ui + 1, nM, nN, nxt);
;         const char* nA = uptr(has_next ? (const char*)A + (size_t)nxt.pm * tstepA + (size_t)nxt.kh * kchunk + E.a_off(nxt.pn) : cA);
;         const char* nB = uptr(has_next ? (const char*)Bt + (size_t)nxt.pn * tstepB + (size_t)nxt.kh * kchunk : cB);
;         for (int t = 0; t < nt; t += 2) {
;             const bool last = (t == nt - 2);
;             const char* a1 = cA + (size_t)(t + 1) * kstep;
;             const char* a2 = last ? nA : cA + (size_t)(t + 2) * kstep; const char* b2 = last ? nB : cB + (size_t)(t + 2) * kstep;
;             const char* a3 = a2 + kstep; const char* b3 = b2 + kstep;
;             G8_LDB(B0, 0, 0); G8_SCHED; G8_LDA(At, 0, 0); G8_STAGE(G8_SA(1, 1), a1 + hstepA, voffA);
;             G8_WAIT_L(8); G8_BAR; G8_WAIT_L(0); G8_MMA(0, 0, At, B0); G8_BAR; G8_SCHED;
;             G8_LDB(B1, 0, 1); G8_STAGE(G8_SB(0, 0), b2, voffB);
;             G8_BAR; G8_WAIT_L(0); G8_MMA(0, 1, At, B1); G8_BAR;
;             G8_LDA(At, 0, 1); G8_STAGE(G8_SA(0, 0), a2, voffA);
;             G8_BAR; G8_WAIT_L(0); G8_MMA(1, 0, At, B0); G8_BAR; G8_SCHED;
.LBB0_187:
	s_ashr_i32 s29, s28, 31
	v_cmp_lt_u64_e32 vcc, s[12:13], v[200:201]
	s_lshl_b64 s[12:13], s[28:29], 19
	v_readlane_b32 s7, v255, 13
	s_add_u32 s7, s7, s12
	v_readlane_b32 s9, v255, 14
	s_addc_u32 s9, s9, s13
	s_and_b64 s[12:13], vcc, exec
	s_cselect_b32 s34, s7, s2
	s_cselect_b32 s35, s9, s3
	s_ashr_i32 s31, s30, 31
	s_lshl_b64 s[12:13], s[30:31], 19
	s_add_u32 s7, s43, s12
	s_addc_u32 s9, s44, s13
	s_and_b64 s[12:13], vcc, exec
	s_cselect_b32 s36, s7, s10
	s_cselect_b32 s37, s9, s11
	s_add_u32 s7, s10, 0x100
	s_addc_u32 s9, s11, 0
	s_add_u32 s2, s2, 0x40080
	s_addc_u32 s3, s3, 0
	s_mov_b32 s16, -2
	ds_read_b128 v[48:51], v240
	ds_read_b128 v[52:55], v240 offset:1024
	ds_read_b128 v[72:75], v240 offset:2048
	ds_read_b128 v[76:79], v240 offset:3072
	s_add_u32 s10, s2, 0xfffc0080
	s_addc_u32 s11, s3, -1
	s_cmp_eq_u32 s16, 12
	s_cselect_b32 s14, s34, s10
	s_cselect_b32 s15, s35, s11
	s_cselect_b32 s10, s36, s7
	s_cselect_b32 s11, s37, s9
	s_add_u32 s12, s14, 0x80
	s_addc_u32 s13, s15, 0
	v_lshl_add_u64 v[176:177], s[2:3], 0, v[192:193]
	s_add_i32 m0, s46, 0xc000
	ds_read_b128 v[88:91], v241
	ds_read_b128 v[100:103], v241 offset:1024
	ds_read_b128 v[112:115], v241 offset:2048
	ds_read_b128 v[124:127], v241 offset:3072
	ds_read_b128 v[136:139], v241 offset:4096
	ds_read_b128 v[140:143], v241 offset:5120
	ds_read_b128 v[160:163], v241 offset:6144
	ds_read_b128 v[164:167], v241 offset:7168
	global_load_lds_dwordx4 v[176:177], off
	v_lshl_add_u64 v[176:177], s[2:3], 0, v[196:197]
	s_add_i32 m0, s46, 0xe000
	s_nop 0
	global_load_lds_dwordx4 v[176:177], off
	s_waitcnt lgkmcnt(8)
	s_barrier
	s_waitcnt lgkmcnt(0)
	s_setprio 1
	s_waitcnt lgkmcnt(0)
	v_mfma_f32_16x16x32_bf16 v[172:175], v[48:51], v[88:91], 0
	v_mfma_f32_16x16x32_bf16 v[168:171], v[72:75], v[88:91], 0
	v_mfma_f32_16x16x32_bf16 v[148:151], v[48:51], v[112:115], 0
	v_mfma_f32_16x16x32_bf16 v[144:147], v[72:75], v[112:115], 0
	v_mfma_f32_16x16x32_bf16 v[120:123], v[48:51], v[136:139], 0
	v_mfma_f32_16x16x32_bf16 v[116:119], v[72:75], v[136:139], 0
	v_mfma_f32_16x16x32_bf16 v[96:99], v[48:51], v[160:163], 0
	v_mfma_f32_16x16x32_bf16 v[92:95], v[72:75], v[160:163], 0
	v_mfma_f32_16x16x32_bf16 v[172:175], v[52:55], v[100:103], v[172:175]
	v_mfma_f32_16x16x32_bf16 v[168:171], v[76:79], v[100:103], v[168:171]
	v_mfma_f32_16x16x32_bf16 v[148:151], v[52:55], v[124:127], v[148:151]
	v_mfma_f32_16x16x32_bf16 v[144:147], v[76:79], v[124:127], v[144:147]
	v_mfma_f32_16x16x32_bf16 v[120:123], v[52:55], v[140:143], v[120:123]
	v_mfma_f32_16x16x32_bf16 v[116:119], v[76:79], v[140:143], v[116:119]
	v_mfma_f32_16x16x32_bf16 v[96:99], v[52:55], v[164:167], v[96:99]
	v_mfma_f32_16x16x32_bf16 v[92:95], v[76:79], v[164:167], v[92:95]
	s_setprio 0
	s_barrier
	s_add_i32 s17, s57, s45
	v_lshl_add_u64 v[206:207], s[10:11], 0, v[194:195]
	s_mov_b32 m0, s17
	ds_read_b128 v[176:179], v242
	ds_read_b128 v[180:183], v242 offset:1024
	ds_read_b128 v[184:187], v242 offset:2048
	ds_read_b128 v[188:191], v242 offset:3072
	global_load_lds_dwordx4 v[206:207], off
	v_lshl_add_u64 v[206:207], s[10:11], 0, v[198:199]
	s_add_i32 m0, s17, 0x2000
	s_nop 0
	global_load_lds_dwordx4 v[206:207], off
	s_barrier
	s_waitcnt lgkmcnt(0)
	s_setprio 1
	s_waitcnt lgkmcnt(0)
	v_mfma_f32_16x16x32_bf16 v[156:159], v[176:179], v[88:91], 0
	v_mfma_f32_16x16x32_bf16 v[88:91], v[184:187], v[88:91], 0
	v_mfma_f32_16x16x32_bf16 v[108:111], v[176:179], v[136:139], 0
	v_mfma_f32_16x16x32_bf16 v[104:107], v[184:187], v[136:139], 0
	v_mfma_f32_16x16x32_bf16 v[84:87], v[176:179], v[160:163], 0
	v_mfma_f32_16x16x32_bf16 v[80:83], v[184:187], v[160:163], 0
	v_mfma_f32_16x16x32_bf16 v[156:159], v[180:183], v[100:103], v[156:159]
	v_mfma_f32_16x16x32_bf16 v[88:91], v[188:191], v[100:103], v[88:91]
	v_mfma_f32_16x16x32_bf16 v[100:103], v[176:179], v[112:115], 0
	v_mfma_f32_16x16x32_bf16 v[112:115], v[184:187], v[112:115], 0
	v_mfma_f32_16x16x32_bf16 v[108:111], v[180:183], v[140:143], v[108:111]
	v_mfma_f32_16x16x32_bf16 v[104:107], v[188:191], v[140:143], v[104:107]
	v_mfma_f32_16x16x32_bf16 v[84:87], v[180:183], v[164:167], v[84:87]
	v_mfma_f32_16x16x32_bf16 v[80:83], v[188:191], v[164:167], v[80:83]
	v_mfma_f32_16x16x32_bf16 v[100:103], v[180:183], v[124:127], v[100:103]
	v_mfma_f32_16x16x32_bf16 v[112:115], v[188:191], v[124:127], v[112:115]
	s_setprio 0
	s_mov_b32 m0, s46
	v_lshl_add_u64 v[206:207], s[14:15], 0, v[192:193]
	s_barrier
	ds_read_b128 v[124:127], v241 offset:16384
	ds_read_b128 v[128:131], v241 offset:17408
	ds_read_b128 v[132:135], v241 offset:18432
	ds_read_b128 v[136:139], v241 offset:19456
	ds_read_b128 v[140:143], v241 offset:20480
	ds_read_b128 v[152:155], v241 offset:21504
	ds_read_b128 v[160:163], v241 offset:22528
	ds_read_b128 v[164:167], v241 offset:23552
	global_load_lds_dwordx4 v[206:207], off
	v_lshl_add_u64 v[206:207], s[14:15], 0, v[196:197]
	s_mov_b32 m0, s47
	s_nop 0
	global_load_lds_dwordx4 v[206:207], off
	s_barrier
	s_waitcnt lgkmcnt(0)
	s_setprio 1
	s_waitcnt lgkmcnt(0)
	v_mfma_f32_16x16x32_bf16 v[68:71], v[48:51], v[124:127], 0
	v_mfma_f32_16x16x32_bf16 v[64:67], v[72:75], v[124:127], 0
	v_mfma_f32_16x16x32_bf16 v[44:47], v[48:51], v[132:135], 0
	v_mfma_f32_16x16x32_bf16 v[40:43], v[72:75], v[132:135], 0
	v_mfma_f32_16x16x32_bf16 v[28:31], v[48:51], v[140:143], 0
	v_mfma_f32_16x16x32_bf16 v[24:27], v[72:75], v[140:143], 0
	v_mfma_f32_16x16x32_bf16 v[12:15], v[48:51], v[160:163], 0
	v_mfma_f32_16x16x32_bf16 v[8:11], v[72:75], v[160:163], 0
	v_mfma_f32_16x16x32_bf16 v[68:71], v[52:55], v[128:131], v[68:71]
	v_mfma_f32_16x16x32_bf16 v[64:67], v[76:79], v[128:131], v[64:67]
	v_mfma_f32_16x16x32_bf16 v[44:47], v[52:55], v[136:139], v[44:47]
	v_mfma_f32_16x16x32_bf16 v[40:43], v[76:79], v[136:139], v[40:43]
	v_mfma_f32_16x16x32_bf16 v[28:31], v[52:55], v[152:155], v[28:31]
	v_mfma_f32_16x16x32_bf16 v[24:27], v[76:79], v[152:155], v[24:27]
	v_mfma_f32_16x16x32_bf16 v[12:15], v[52:55], v[164:167], v[12:15]
	v_mfma_f32_16x16x32_bf16 v[8:11], v[76:79], v[164:167], v[8:11]
	s_setprio 0
	s_barrier
; #define G8_STAGE(bufoff, gbase, voff) do { const char* _gb = uptr((const char*)(gbase)); _Pragma("unroll") for (int _i = 0; _i < 2; ++_i) \
;         __builtin_amdgcn_global_load_lds((const unsigned*)(_gb + (voff)[_i]), (LAS unsigned*)(lds + (bufoff) + ldsw + _i * 8192), 16, 0, 0); } while (0)
; #define G8_LDA(dst, b, h) do { _Pragma("unroll") for (int m = 0; m < 4; ++m) _Pragma("unroll") for (int k = 0; k < 2; ++k) dst[m][k] = *(const LAS bf16x8*)(lds + G8_SA(b, h) + aoff + m * 2048 + k * 1024); } while (0)
; #define G8_LDB(dst, b, h) do { _Pragma("unroll") for (int n = 0; n < 2; ++n) _Pragma("unroll") for (int k = 0; k < 2; ++k) dst[n][k] = *(const LAS bf16x8*)(lds + G8_SB(b, h) + boff + n * 2048 + k * 1024); } while (0)
; #define G8_MMA(ai, bj, At, Bt_) do { __builtin_amdgcn_s_setprio(1); _Pragma("unroll") for (int m = 0; m < 4; ++m) _Pragma("unroll") for (int n = 0; n < 2; ++n) _Pragma("unroll") for (int k = 0; k < 2; ++k) \
;         acc[ai][bj][m][n] = __builtin_amdgcn_mfma_f32_16x16x32_bf16(Bt_[n][k], At[m][k], acc[ai][bj][m][n], 0, 0, 0); __builtin_amdgcn_s_setprio(0); } while (0)
; #define G8_WAIT_V(n) asm volatile("s_waitcnt vmcnt(" #n ")" ::: "memory")
; #define G8_WAIT_L(n) asm volatile("s_waitcnt lgkmcnt(" #n ")" ::: "memory")
; #define G8_BAR __builtin_amdgcn_s_barrier()
; #define G8_SCHED __builtin_amdgcn_sched_barrier(0)
;     ...
;             G8_STAGE(G8_SB(0, 1), b2 + hstepB, voffB);
;             G8_WAIT_V(6); G8_BAR; G8_MMA(1, 1, At, B1); G8_BAR;
;             G8_LDB(B0, 1, 0); G8_SCHED; G8_LDA(At, 1, 0); G8_STAGE(G8_SA(0, 1), a2 + hstepA, voffA);
;             G8_WAIT_L(8); G8_BAR; G8_WAIT_L(0); G8_MMA(0, 0, At, B0); G8_BAR; G8_SCHED;
;             G8_LDB(B1, 1, 1); G8_STAGE(G8_SB(1, 0), b3, voffB);
;             G8_BAR; G8_WAIT_L(0); G8_MMA(0, 1, At, B1); G8_BAR;
;             G8_LDA(At, 1, 1); G8_STAGE(G8_SA(1, 0), a3, voffA);
	s_add_u32 s38, s10, 0x40000
	s_addc_u32 s39, s11, 0
	s_add_i32 s17, s58, s45
	v_lshl_add_u64 v[48:49], s[38:39], 0, v[194:195]
	s_mov_b32 m0, s17
	s_nop 0
	global_load_lds_dwordx4 v[48:49], off
	v_lshl_add_u64 v[48:49], s[38:39], 0, v[198:199]
	s_add_i32 m0, s17, 0x2000
	s_nop 0
	global_load_lds_dwordx4 v[48:49], off
	s_waitcnt vmcnt(6)
	s_barrier
	s_setprio 1
	v_mfma_f32_16x16x32_bf16 v[36:39], v[176:179], v[132:135], 0
	v_mfma_f32_16x16x32_bf16 v[32:35], v[184:187], v[132:135], 0
	v_mfma_f32_16x16x32_bf16 v[20:23], v[176:179], v[140:143], 0
	v_mfma_f32_16x16x32_bf16 v[16:19], v[184:187], v[140:143], 0
	v_mfma_f32_16x16x32_bf16 v[4:7], v[176:179], v[160:163], 0
	v_mfma_f32_16x16x32_bf16 v[0:3], v[184:187], v[160:163], 0
	v_mfma_f32_16x16x32_bf16 v[48:51], v[176:179], v[124:127], 0
	v_mfma_f32_16x16x32_bf16 v[52:55], v[184:187], v[124:127], 0
	v_mfma_f32_16x16x32_bf16 v[36:39], v[180:183], v[136:139], v[36:39]
	v_mfma_f32_16x16x32_bf16 v[32:35], v[188:191], v[136:139], v[32:35]
	v_mfma_f32_16x16x32_bf16 v[20:23], v[180:183], v[152:155], v[20:23]
	v_mfma_f32_16x16x32_bf16 v[16:19], v[188:191], v[152:155], v[16:19]
	v_mfma_f32_16x16x32_bf16 v[4:7], v[180:183], v[164:167], v[4:7]
	v_mfma_f32_16x16x32_bf16 v[0:3], v[188:191], v[164:167], v[0:3]
	v_mfma_f32_16x16x32_bf16 v[48:51], v[180:183], v[128:131], v[48:51]
	v_mfma_f32_16x16x32_bf16 v[52:55], v[188:191], v[128:131], v[52:55]
	s_setprio 0
	s_add_i32 s17, 0, 0x18000
	v_add_u32_e32 v76, s17, v237
	s_barrier
	ds_read_b128 v[56:59], v76
	ds_read_b128 v[60:63], v76 offset:1024
	ds_read_b128 v[72:75], v76 offset:2048
	ds_read_b128 v[76:79], v76 offset:3072
	s_add_u32 s14, s14, 0x40000
	s_addc_u32 s15, s15, 0
	s_mov_b32 m0, s48
	v_lshl_add_u64 v[132:133], s[14:15], 0, v[192:193]
	ds_read_b128 v[124:127], v241 offset:32768
	ds_read_b128 v[128:131], v241 offset:33792
	ds_read_b128 v[136:139], v241 offset:34816
	ds_read_b128 v[140:143], v241 offset:35840
	ds_read_b128 v[160:163], v241 offset:36864
	ds_read_b128 v[164:167], v241 offset:37888
	ds_read_b128 v[176:179], v241 offset:38912
	ds_read_b128 v[180:183], v241 offset:39936
	global_load_lds_dwordx4 v[132:133], off
	v_lshl_add_u64 v[132:133], s[14:15], 0, v[196:197]
	s_mov_b32 m0, s49
	s_nop 0
	global_load_lds_dwordx4 v[132:133], off
	s_waitcnt lgkmcnt(8)
	s_barrier
	s_waitcnt lgkmcnt(0)
	s_setprio 1
	s_waitcnt lgkmcnt(0)
	v_mfma_f32_16x16x32_bf16 v[132:135], v[56:59], v[124:127], v[172:175]
	v_mfma_f32_16x16x32_bf16 v[172:175], v[60:63], v[128:131], v[132:135]
	v_mfma_f32_16x16x32_bf16 v[132:135], v[72:75], v[124:127], v[168:171]
	v_mfma_f32_16x16x32_bf16 v[168:171], v[76:79], v[128:131], v[132:135]
	v_mfma_f32_16x16x32_bf16 v[132:135], v[56:59], v[136:139], v[148:151]
	v_mfma_f32_16x16x32_bf16 v[148:151], v[60:63], v[140:143], v[132:135]
	v_mfma_f32_16x16x32_bf16 v[132:135], v[72:75], v[136:139], v[144:147]
	v_mfma_f32_16x16x32_bf16 v[120:123], v[56:59], v[160:163], v[120:123]
	v_mfma_f32_16x16x32_bf16 v[116:119], v[72:75], v[160:163], v[116:119]
	v_mfma_f32_16x16x32_bf16 v[96:99], v[56:59], v[176:179], v[96:99]
	v_mfma_f32_16x16x32_bf16 v[92:95], v[72:75], v[176:179], v[92:95]
	v_mfma_f32_16x16x32_bf16 v[144:147], v[76:79], v[140:143], v[132:135]
	v_mfma_f32_16x16x32_bf16 v[120:123], v[60:63], v[164:167], v[120:123]
	v_mfma_f32_16x16x32_bf16 v[116:119], v[76:79], v[164:167], v[116:119]
	v_mfma_f32_16x16x32_bf16 v[96:99], v[60:63], v[180:183], v[96:99]
	v_mfma_f32_16x16x32_bf16 v[92:95], v[76:79], v[180:183], v[92:95]
	s_setprio 0
	s_barrier
	s_add_i32 s24, 0, 0x1c000
	s_add_u32 s14, s10, 0x80
	v_add_u32_e32 v132, s24, v237
	s_addc_u32 s15, s11, 0
	s_add_i32 s17, s17, s45
	ds_read_b128 v[184:187], v132
	ds_read_b128 v[188:191], v132 offset:1024
	ds_read_b128 v[206:209], v132 offset:2048
	ds_read_b128 v[210:213], v132 offset:3072
	v_lshl_add_u64 v[132:133], s[14:15], 0, v[194:195]
	s_mov_b32 m0, s17
	s_nop 0
	global_load_lds_dwordx4 v[132:133], off
	v_lshl_add_u64 v[132:133], s[14:15], 0, v[198:199]
	s_add_i32 m0, s17, 0x2000
	s_nop 0
	global_load_lds_dwordx4 v[132:133], off
	s_barrier
; #define G8_STAGE(bufoff, gbase, voff) do { const char* _gb = uptr((const char*)(gbase)); _Pragma("unroll") for (int _i = 0; _i < 2; ++_i) \
;         __builtin_amdgcn_global_load_lds((const unsigned*)(_gb + (voff)[_i]), (LAS unsigned*)(lds + (bufoff) + ldsw + _i * 8192), 16, 0, 0); } while (0)
; #define G8_LDA(dst, b, h) do { _Pragma("unroll") for (int m = 0; m < 4; ++m) _Pragma("unroll") for (int k = 0; k < 2; ++k) dst[m][k] = *(const LAS bf16x8*)(lds + G8_SA(b, h) + aoff + m * 2048 + k * 1024); } while (0)
; #define G8_MMA(ai, bj, At, Bt_) do { __builtin_amdgcn_s_setprio(1); _Pragma("unroll") for (int m = 0; m < 4; ++m) _Pragma("unroll") for (int n = 0; n < 2; ++n) _Pragma("unroll") for (int k = 0; k < 2; ++k) \
;         acc[ai][bj][m][n] = __builtin_amdgcn_mfma_f32_16x16x32_bf16(Bt_[n][k], At[m][k], acc[ai][bj][m][n], 0, 0, 0); __builtin_amdgcn_s_setprio(0); } while (0)
; #define G8_WAIT_V(n) asm volatile("s_waitcnt vmcnt(" #n ")" ::: "memory")
; #define G8_WAIT_L(n) asm volatile("s_waitcnt lgkmcnt(" #n ")" ::: "memory")
; #define G8_BAR __builtin_amdgcn_s_barrier()
; #define G8_SCHED __builtin_amdgcn_sched_barrier(0)
;     ...
;             G8_LDA(At, 1, 1); G8_STAGE(G8_SA(1, 0), a3, voffA);
;             G8_BAR; G8_WAIT_L(0); G8_MMA(1, 0, At, B0); G8_BAR; G8_SCHED;
;             G8_STAGE(G8_SB(1, 1), b3 + hstepB, voffB);
;             G8_WAIT_V(6); G8_BAR; G8_MMA(1, 1, At, B1); G8_BAR;
;         }
	s_waitcnt lgkmcnt(0)
	s_setprio 1
	s_waitcnt lgkmcnt(0)
	v_mfma_f32_16x16x32_bf16 v[88:91], v[206:209], v[124:127], v[88:91]
	v_mfma_f32_16x16x32_bf16 v[132:135], v[184:187], v[124:127], v[156:159]
	v_mfma_f32_16x16x32_bf16 v[152:155], v[210:213], v[128:131], v[88:91]
	v_mfma_f32_16x16x32_bf16 v[88:91], v[184:187], v[136:139], v[100:103]
	v_mfma_f32_16x16x32_bf16 v[156:159], v[188:191], v[128:131], v[132:135]
	v_mfma_f32_16x16x32_bf16 v[132:135], v[188:191], v[140:143], v[88:91]
	v_mfma_f32_16x16x32_bf16 v[88:91], v[206:209], v[136:139], v[112:115]
	v_mfma_f32_16x16x32_bf16 v[128:131], v[210:213], v[140:143], v[88:91]
	v_mfma_f32_16x16x32_bf16 v[88:91], v[184:187], v[160:163], v[108:111]
	v_mfma_f32_16x16x32_bf16 v[108:111], v[188:191], v[164:167], v[88:91]
	v_mfma_f32_16x16x32_bf16 v[88:91], v[206:209], v[160:163], v[104:107]
	v_mfma_f32_16x16x32_bf16 v[84:87], v[184:187], v[176:179], v[84:87]
	v_mfma_f32_16x16x32_bf16 v[80:83], v[206:209], v[176:179], v[80:83]
	v_mfma_f32_16x16x32_bf16 v[104:107], v[210:213], v[164:167], v[88:91]
	v_mfma_f32_16x16x32_bf16 v[84:87], v[188:191], v[180:183], v[84:87]
	v_mfma_f32_16x16x32_bf16 v[80:83], v[210:213], v[180:183], v[80:83]
	s_setprio 0
	s_mov_b32 m0, s53
	v_lshl_add_u64 v[176:177], s[12:13], 0, v[192:193]
	s_barrier
	ds_read_b128 v[88:91], v241 offset:49152
	ds_read_b128 v[100:103], v241 offset:50176
	ds_read_b128 v[112:115], v241 offset:51200
	ds_read_b128 v[124:127], v241 offset:52224
	ds_read_b128 v[136:139], v241 offset:53248
	ds_read_b128 v[140:143], v241 offset:54272
	ds_read_b128 v[160:163], v241 offset:55296
	ds_read_b128 v[164:167], v241 offset:56320
	global_load_lds_dwordx4 v[176:177], off
	v_lshl_add_u64 v[176:177], s[12:13], 0, v[196:197]
	s_mov_b32 m0, s33
	s_nop 0
	global_load_lds_dwordx4 v[176:177], off
	s_barrier
	s_waitcnt lgkmcnt(0)
	s_setprio 1
	s_waitcnt lgkmcnt(0)
	v_mfma_f32_16x16x32_bf16 v[68:71], v[56:59], v[88:91], v[68:71]
	v_mfma_f32_16x16x32_bf16 v[64:67], v[72:75], v[88:91], v[64:67]
	v_mfma_f32_16x16x32_bf16 v[44:47], v[56:59], v[112:115], v[44:47]
	v_mfma_f32_16x16x32_bf16 v[40:43], v[72:75], v[112:115], v[40:43]
	v_mfma_f32_16x16x32_bf16 v[28:31], v[56:59], v[136:139], v[28:31]
	v_mfma_f32_16x16x32_bf16 v[24:27], v[72:75], v[136:139], v[24:27]
	v_mfma_f32_16x16x32_bf16 v[12:15], v[56:59], v[160:163], v[12:15]
	v_mfma_f32_16x16x32_bf16 v[8:11], v[72:75], v[160:163], v[8:11]
	v_mfma_f32_16x16x32_bf16 v[68:71], v[60:63], v[100:103], v[68:71]
	v_mfma_f32_16x16x32_bf16 v[64:67], v[76:79], v[100:103], v[64:67]
	v_mfma_f32_16x16x32_bf16 v[44:47], v[60:63], v[124:127], v[44:47]
	v_mfma_f32_16x16x32_bf16 v[40:43], v[76:79], v[124:127], v[40:43]
	v_mfma_f32_16x16x32_bf16 v[28:31], v[60:63], v[140:143], v[28:31]
	v_mfma_f32_16x16x32_bf16 v[24:27], v[76:79], v[140:143], v[24:27]
	v_mfma_f32_16x16x32_bf16 v[12:15], v[60:63], v[164:167], v[12:15]
	v_mfma_f32_16x16x32_bf16 v[8:11], v[76:79], v[164:167], v[8:11]
	s_setprio 0
	s_barrier
	s_add_u32 s10, s10, 0x40080
	s_addc_u32 s11, s11, 0
	s_add_i32 s12, s24, s45
	v_lshl_add_u64 v[56:57], s[10:11], 0, v[194:195]
	s_mov_b32 m0, s12
	s_nop 0
	global_load_lds_dwordx4 v[56:57], off
	v_lshl_add_u64 v[56:57], s[10:11], 0, v[198:199]
	s_add_i32 m0, s12, 0x2000
	s_nop 0
	global_load_lds_dwordx4 v[56:57], off
	s_waitcnt vmcnt(6)
	s_barrier
	s_setprio 1
	v_mfma_f32_16x16x32_bf16 v[48:51], v[184:187], v[88:91], v[48:51]
	v_mfma_f32_16x16x32_bf16 v[60:63], v[188:191], v[100:103], v[48:51]
	v_mfma_f32_16x16x32_bf16 v[48:51], v[206:209], v[88:91], v[52:55]
	v_mfma_f32_16x16x32_bf16 v[36:39], v[184:187], v[112:115], v[36:39]
	v_mfma_f32_16x16x32_bf16 v[32:35], v[206:209], v[112:115], v[32:35]
	v_mfma_f32_16x16x32_bf16 v[20:23], v[184:187], v[136:139], v[20:23]
	v_mfma_f32_16x16x32_bf16 v[16:19], v[206:209], v[136:139], v[16:19]
	v_mfma_f32_16x16x32_bf16 v[4:7], v[184:187], v[160:163], v[4:7]
	v_mfma_f32_16x16x32_bf16 v[0:3], v[206:209], v[160:163], v[0:3]
	v_mfma_f32_16x16x32_bf16 v[56:59], v[210:213], v[100:103], v[48:51]
	v_mfma_f32_16x16x32_bf16 v[36:39], v[188:191], v[124:127], v[36:39]
	v_mfma_f32_16x16x32_bf16 v[32:35], v[210:213], v[124:127], v[32:35]
	v_mfma_f32_16x16x32_bf16 v[20:23], v[188:191], v[140:143], v[20:23]
	v_mfma_f32_16x16x32_bf16 v[16:19], v[210:213], v[140:143], v[16:19]
	v_mfma_f32_16x16x32_bf16 v[4:7], v[188:191], v[164:167], v[4:7]
	v_mfma_f32_16x16x32_bf16 v[0:3], v[210:213], v[164:167], v[0:3]
	s_setprio 0
	s_add_i32 s16, s16, 2
	s_add_u32 s7, s7, 0x100
	s_addc_u32 s9, s9, 0
	s_add_u32 s2, s2, 0x100
	s_addc_u32 s3, s3, 0
	s_cmp_gt_u32 s16, 13
	s_barrier
